# P4 rowpass_mid: the 16 F-row loads issued together with counted waits (plus pool, qk, epi8, p12lds)
# speedup vs baseline: 1.0088x; 1.0088x over previous
.LBB0_322:
	s_ashr_i32 s0, s25, 31
	s_lshr_b32 s0, s0, 21
	s_add_i32 s0, s25, s0
	s_ashr_i32 s0, s0, 11
	s_add_u32 s8, s84, s36
	s_addc_u32 s1, s85, s37
	s_and_b32 s9, s1, 0xffff
	buffer_load_dwordx2 v[76:77], v153, s[8:11], 0 offen nt
	buffer_load_dwordx2 v[176:177], v153, s[8:11], s29 offen nt
	buffer_load_dwordx2 v[178:179], v153, s[8:11], s30 offen nt
	buffer_load_dwordx2 v[180:181], v153, s[8:11], s31 offen nt
	buffer_load_dwordx2 v[182:183], v153, s[8:11], s33 offen nt
	buffer_load_dwordx2 v[184:185], v153, s[8:11], s35 offen nt
	buffer_load_dwordx2 v[186:187], v153, s[8:11], s53 offen nt
	buffer_load_dwordx2 v[188:189], v153, s[8:11], s54 offen nt
	buffer_load_dwordx2 v[190:191], v153, s[8:11], s55 offen nt
	buffer_load_dwordx2 v[192:193], v153, s[8:11], s73 offen nt
	buffer_load_dwordx2 v[194:195], v153, s[8:11], s76 offen nt
	buffer_load_dwordx2 v[196:197], v153, s[8:11], s77 offen nt
	buffer_load_dwordx2 v[198:199], v153, s[8:11], s94 offen nt
	buffer_load_dwordx2 v[200:201], v153, s[8:11], s95 offen nt
	buffer_load_dwordx2 v[202:203], v153, s[8:11], s78 offen nt
	buffer_load_dwordx2 v[204:205], v153, s[8:11], s79 offen nt
	s_add_u32 s64, s39, s36
	s_addc_u32 s1, s46, s37
	s_mul_i32 s7, s0, 0x24000
	s_mul_hi_i32 s6, s0, 0x24000
	s_add_u32 s0, s90, s7
	s_addc_u32 s20, s91, s6
	s_add_u32 s68, s0, 0x8000
	s_addc_u32 s0, s20, 0
	s_add_u32 s60, s52, s7
	v_readlane_b32 s7, v250, 40
	s_addc_u32 s7, s7, s6
	s_add_u32 s56, s60, 0x4000
	s_addc_u32 s6, s7, 0
	s_and_b32 s21, s27, 0xffff
	s_mov_b32 s20, s26
	s_mov_b32 s23, s11
	s_and_b32 s69, s0, 0xffff
	s_mov_b32 s70, s22
	s_mov_b32 s71, s11
	s_and_b32 s61, s7, 0xffff
	s_mov_b32 s7, 0xf800000
	s_and_b32 s65, s1, 0xffff
	s_mov_b32 s66, s10
	s_mov_b32 s67, s11
	s_and_b32 s57, s6, 0xffff
	s_mov_b32 s6, s14
	s_mov_b32 s62, s22
	s_mov_b32 s63, s11
	s_mov_b32 s58, s22
	s_mov_b32 s59, s11
	s_waitcnt vmcnt(15)
	v_and_b32_e32 v73, 0xffff0000, v77
	v_lshlrev_b32_e32 v72, 16, v77
	v_mul_f32_e32 v0, v73, v73
	v_pk_fma_f32 v[74:75], v[72:73], v[72:73], v[0:1] op_sel_hi:[1,1,0]
	s_nop 0
	v_lshlrev_b32_e32 v146, 16, v76
	v_and_b32_e32 v147, 0xffff0000, v76
	v_mov_b32_e32 v174, v74
	s_waitcnt vmcnt(14)
	v_and_b32_e32 v71, 0xffff0000, v177
	v_and_b32_e32 v70, 0xffff0000, v176
	v_lshlrev_b32_e32 v69, 16, v177
	v_lshlrev_b32_e32 v68, 16, v176
	v_pk_mul_f32 v[0:1], v[70:71], v[70:71]
	s_nop 0
	v_pk_fma_f32 v[136:137], v[68:69], v[68:69], v[0:1]
	s_nop 0
	v_pk_add_f32 v[136:137], v[136:137], v[136:137] op_sel:[0,1] op_sel_hi:[1,0]
	s_waitcnt vmcnt(13)
	v_lshlrev_b32_e32 v64, 16, v178
	v_and_b32_e32 v65, 0xffff0000, v178
	v_lshlrev_b32_e32 v66, 16, v179
	v_and_b32_e32 v67, 0xffff0000, v179
	s_nop 0
	v_mul_f32_e32 v76, v65, v65
	s_waitcnt vmcnt(12)
	v_lshlrev_b32_e32 v133, 16, v180
	v_and_b32_e32 v131, 0xffff0000, v180
	v_lshlrev_b32_e32 v134, 16, v181
	v_and_b32_e32 v135, 0xffff0000, v181
	s_nop 0
	v_mul_f32_e32 v112, v134, v134
	v_mul_f32_e32 v98, v135, v135
	v_mov_b32_e32 v175, v133
	v_mul_f32_e32 v78, v131, v131
	v_mov_b32_e32 v137, v78
	s_waitcnt vmcnt(11)
	v_and_b32_e32 v129, 0xffff0000, v183
	v_and_b32_e32 v128, 0xffff0000, v182
	v_lshlrev_b32_e32 v127, 16, v183
	v_lshlrev_b32_e32 v126, 16, v182
	v_pk_mul_f32 v[0:1], v[128:129], v[128:129]
	s_nop 0
	v_pk_fma_f32 v[0:1], v[126:127], v[126:127], v[0:1]
	s_nop 0
	v_pk_add_f32 v[138:139], v[0:1], v[0:1] op_sel:[0,1] op_sel_hi:[1,0]
	s_nop 0
	s_waitcnt vmcnt(10)
	v_and_b32_e32 v125, 0xffff0000, v185
	v_and_b32_e32 v124, 0xffff0000, v184
	v_lshlrev_b32_e32 v123, 16, v185
	v_lshlrev_b32_e32 v122, 16, v184
	v_pk_mul_f32 v[0:1], v[124:125], v[124:125]
	s_nop 0
	v_pk_fma_f32 v[140:141], v[122:123], v[122:123], v[0:1]
	s_nop 0
	s_waitcnt vmcnt(9)
	v_lshlrev_b32_e32 v118, 16, v186
	v_and_b32_e32 v119, 0xffff0000, v186
	v_lshlrev_b32_e32 v120, 16, v187
	v_and_b32_e32 v121, 0xffff0000, v187
	s_nop 0
	s_waitcnt vmcnt(8)
	v_lshlrev_b32_e32 v115, 16, v188
	v_and_b32_e32 v113, 0xffff0000, v188
	v_lshlrev_b32_e32 v116, 16, v189
	v_and_b32_e32 v117, 0xffff0000, v189
	s_nop 0
	v_mul_f32_e32 v163, v116, v116
	v_mul_f32_e32 v114, v117, v117
	v_mul_f32_e32 v96, v113, v113
	s_waitcnt vmcnt(7)
	v_and_b32_e32 v111, 0xffff0000, v191
	v_and_b32_e32 v110, 0xffff0000, v190
	v_lshlrev_b32_e32 v109, 16, v191
	v_lshlrev_b32_e32 v108, 16, v190
	v_pk_mul_f32 v[0:1], v[110:111], v[110:111]
	s_nop 0
	v_pk_fma_f32 v[0:1], v[108:109], v[108:109], v[0:1]
	s_nop 0
	v_pk_add_f32 v[142:143], v[0:1], v[0:1] op_sel:[0,1] op_sel_hi:[1,0]
	s_nop 0
	s_waitcnt vmcnt(6)
	v_and_b32_e32 v107, 0xffff0000, v193
	v_and_b32_e32 v106, 0xffff0000, v192
	v_lshlrev_b32_e32 v105, 16, v193
	v_lshlrev_b32_e32 v104, 16, v192
	v_pk_mul_f32 v[0:1], v[106:107], v[106:107]
	s_nop 0
	v_pk_fma_f32 v[144:145], v[104:105], v[104:105], v[0:1]
	s_nop 0
	s_waitcnt vmcnt(5)
	v_lshlrev_b32_e32 v100, 16, v194
	v_and_b32_e32 v101, 0xffff0000, v194
	v_lshlrev_b32_e32 v102, 16, v195
	v_and_b32_e32 v103, 0xffff0000, v195
	s_nop 0
	s_waitcnt vmcnt(4)
	v_lshlrev_b32_e32 v99, 16, v196
	v_and_b32_e32 v97, 0xffff0000, v196
	v_lshlrev_b32_e32 v94, 16, v197
	v_and_b32_e32 v95, 0xffff0000, v197
	s_nop 0
	v_mul_f32_e32 v166, v94, v94
	v_mul_f32_e32 v165, v95, v95
	v_mul_f32_e32 v130, v97, v97
	s_waitcnt vmcnt(3)
	v_and_b32_e32 v93, 0xffff0000, v199
	v_and_b32_e32 v92, 0xffff0000, v198
	v_lshlrev_b32_e32 v91, 16, v199
	v_lshlrev_b32_e32 v90, 16, v198
	v_pk_mul_f32 v[0:1], v[92:93], v[92:93]
	s_nop 0
	v_pk_fma_f32 v[0:1], v[90:91], v[90:91], v[0:1]
	s_nop 0
	v_pk_add_f32 v[148:149], v[0:1], v[0:1] op_sel:[0,1] op_sel_hi:[1,0]
	s_nop 0
	s_waitcnt vmcnt(2)
	v_and_b32_e32 v89, 0xffff0000, v201
	v_and_b32_e32 v88, 0xffff0000, v200
	v_lshlrev_b32_e32 v87, 16, v201
	v_lshlrev_b32_e32 v86, 16, v200
	v_pk_mul_f32 v[0:1], v[88:89], v[88:89]
	s_nop 0
	v_pk_fma_f32 v[150:151], v[86:87], v[86:87], v[0:1]
	s_nop 0
	s_waitcnt vmcnt(1)
	v_lshlrev_b32_e32 v82, 16, v202
	v_and_b32_e32 v83, 0xffff0000, v202
	v_lshlrev_b32_e32 v84, 16, v203
	v_and_b32_e32 v85, 0xffff0000, v203
	s_nop 0
	s_add_u32 s8, s38, s36
	s_waitcnt vmcnt(0)
	v_and_b32_e32 v77, 0xffff0000, v204
	v_pk_fma_f32 v[170:171], v[64:65], v[64:65], v[76:77] op_sel_hi:[1,1,0]
	v_mul_f32_e32 v76, v67, v67
	v_pk_fma_f32 v[172:173], v[66:67], v[66:67], v[76:77] op_sel_hi:[1,1,0]
	v_mov_b32_e32 v171, v112
	v_mov_b32_e32 v173, v98
	v_mul_f32_e32 v76, v147, v147
	v_pk_add_f32 v[170:171], v[170:171], v[172:173]
	v_pk_fma_f32 v[172:173], v[146:147], v[146:147], v[76:77] op_sel_hi:[1,1,0]
	v_mul_f32_e32 v76, v119, v119
	v_mov_b32_e32 v132, v172
	v_pk_add_f32 v[74:75], v[172:173], v[74:75]
	v_pk_mul_f32 v[172:173], v[132:133], v[174:175]
	v_lshlrev_b32_e32 v80, 16, v205
	v_mov_b32_e32 v75, v173
	v_pk_add_f32 v[74:75], v[74:75], v[136:137]
	v_pk_fma_f32 v[136:137], v[118:119], v[118:119], v[76:77] op_sel_hi:[1,1,0]
	v_mul_f32_e32 v76, v121, v121
	v_pk_add_f32 v[74:75], v[74:75], v[170:171]
	v_pk_fma_f32 v[170:171], v[120:121], v[120:121], v[76:77] op_sel_hi:[1,1,0]
	v_mov_b32_e32 v137, v163
	v_mov_b32_e32 v171, v114
	v_pk_add_f32 v[74:75], v[74:75], v[74:75] op_sel:[0,1] op_sel_hi:[1,0]
	v_pk_add_f32 v[136:137], v[136:137], v[170:171]
	v_mov_b32_e32 v114, v74
	v_mov_b32_e32 v170, v138
	v_mov_b32_e32 v171, v115
	v_pk_add_f32 v[74:75], v[74:75], v[138:139]
	v_pk_mul_f32 v[138:139], v[114:115], v[170:171]
	v_mul_f32_e32 v76, v101, v101
	v_mov_b32_e32 v75, v139
	v_pk_add_f32 v[138:139], v[140:141], v[140:141] op_sel:[0,1] op_sel_hi:[1,0]
	v_and_b32_e32 v81, 0xffff0000, v205
	v_mov_b32_e32 v139, v96
	v_pk_add_f32 v[74:75], v[74:75], v[138:139]
	v_mul_f32_e32 v168, v80, v80
	v_pk_add_f32 v[74:75], v[74:75], v[136:137]
	v_pk_fma_f32 v[136:137], v[100:101], v[100:101], v[76:77] op_sel_hi:[1,1,0]
	v_mul_f32_e32 v76, v103, v103
	v_pk_fma_f32 v[138:139], v[102:103], v[102:103], v[76:77] op_sel_hi:[1,1,0]
	v_mov_b32_e32 v137, v166
	v_mov_b32_e32 v139, v165
	v_pk_add_f32 v[74:75], v[74:75], v[74:75] op_sel:[0,1] op_sel_hi:[1,0]
	v_pk_add_f32 v[136:137], v[136:137], v[138:139]
	v_mov_b32_e32 v98, v74
	v_mov_b32_e32 v138, v142
	v_mov_b32_e32 v139, v99
	v_pk_add_f32 v[74:75], v[74:75], v[142:143]
	v_pk_mul_f32 v[138:139], v[98:99], v[138:139]
	v_mul_f32_e32 v76, v83, v83
	v_mov_b32_e32 v75, v139
	v_pk_add_f32 v[138:139], v[144:145], v[144:145] op_sel:[0,1] op_sel_hi:[1,0]
	v_mul_f32_e32 v167, v81, v81
	v_mov_b32_e32 v139, v130
	v_pk_add_f32 v[74:75], v[74:75], v[138:139]
	v_lshlrev_b32_e32 v79, 16, v204
	v_pk_add_f32 v[74:75], v[74:75], v[136:137]
	v_pk_fma_f32 v[136:137], v[82:83], v[82:83], v[76:77] op_sel_hi:[1,1,0]
	v_mul_f32_e32 v76, v85, v85
	v_pk_fma_f32 v[138:139], v[84:85], v[84:85], v[76:77] op_sel_hi:[1,1,0]
	v_mov_b32_e32 v137, v168
	v_mov_b32_e32 v139, v167
	v_pk_add_f32 v[74:75], v[74:75], v[74:75] op_sel:[0,1] op_sel_hi:[1,0]
	v_pk_add_f32 v[136:137], v[136:137], v[138:139]
	v_mov_b32_e32 v78, v74
	v_mov_b32_e32 v138, v148
	v_mov_b32_e32 v139, v79
	v_pk_add_f32 v[74:75], v[74:75], v[148:149]
	v_pk_mul_f32 v[138:139], v[78:79], v[138:139]
	v_mul_f32_e32 v164, v77, v77
	v_mov_b32_e32 v75, v139
	v_pk_add_f32 v[138:139], v[150:151], v[150:151] op_sel:[0,1] op_sel_hi:[1,0]
	buffer_load_dwordx4 v[60:63], v152, s[20:23], 0 offen nt
	buffer_load_dwordx4 v[56:59], v152, s[20:23], s30 offen nt
	buffer_load_dwordx4 v[52:55], v152, s[20:23], s33 offen nt
	buffer_load_dwordx4 v[48:51], v152, s[20:23], s53 offen nt
	buffer_load_dwordx4 v[44:47], v152, s[20:23], s55 offen nt
	buffer_load_dwordx4 v[40:43], v152, s[20:23], s76 offen nt
	buffer_load_dwordx4 v[36:39], v152, s[20:23], s94 offen nt
	buffer_load_dwordx4 v[32:35], v152, s[20:23], s78 offen nt
	buffer_load_dwordx4 v[28:31], v152, s[20:23], s10 offen nt
	buffer_load_dwordx4 v[24:27], v152, s[20:23], s88 offen nt
	buffer_load_dwordx4 v[20:23], v152, s[20:23], s89 offen nt
	buffer_load_dwordx4 v[16:19], v152, s[20:23], s82 offen nt
	buffer_load_dwordx4 v[12:15], v152, s[20:23], s83 offen nt
	buffer_load_dwordx4 v[8:11], v152, s[20:23], s96 offen nt
	buffer_load_dwordx4 v[4:7], v152, s[20:23], s97 offen nt
	buffer_load_dwordx4 v[0:3], v152, s[20:23], s81 offen nt
	v_mov_b32_e32 v139, v164
	v_pk_add_f32 v[74:75], v[74:75], v[138:139]
	v_mov_b32_e32 v130, v133
	v_pk_add_f32 v[74:75], v[74:75], v[136:137]
	buffer_load_dwordx4 v[136:139], v152, s[12:15], 0 offen
	buffer_load_dwordx4 v[140:143], v152, s[68:71], 0 offen
	v_add_f32_e32 v74, v74, v75
	ds_bpermute_b32 v75, v154, v74
	v_mov_b32_e32 v112, v115
	s_waitcnt lgkmcnt(0)
	v_add_f32_e32 v74, v74, v75
	ds_bpermute_b32 v75, v155, v74
	s_waitcnt lgkmcnt(0)
	v_add_f32_e32 v74, v74, v75
	ds_bpermute_b32 v75, v156, v74
	s_waitcnt lgkmcnt(0)
	v_add_f32_e32 v74, v74, v75
	ds_bpermute_b32 v75, v157, v74
	s_waitcnt lgkmcnt(0)
	v_add_f32_e32 v74, v74, v75
	ds_bpermute_b32 v75, v158, v74
	s_waitcnt lgkmcnt(0)
	v_add_f32_e32 v74, v74, v75
	ds_bpermute_b32 v75, v159, v74
	s_waitcnt lgkmcnt(0)
	v_add_f32_e32 v74, v74, v75
	v_fmamk_f32 v74, v74, 0x39800000, v160
	v_cmp_gt_f32_e32 vcc, s7, v74
	v_mul_f32_e32 v75, 0x4f800000, v74
	s_nop 0
	v_cndmask_b32_e32 v74, v74, v75, vcc
	v_sqrt_f32_e32 v75, v74
	s_nop 0
	v_add_u32_e32 v76, -1, v75
	v_fma_f32 v78, -v76, v75, v74
	v_cmp_ge_f32_e64 s[0:1], 0, v78
	v_add_u32_e32 v78, 1, v75
	s_nop 0
	v_cndmask_b32_e64 v76, v75, v76, s[0:1]
	v_fma_f32 v75, -v78, v75, v74
	v_cmp_lt_f32_e64 s[0:1], 0, v75
	s_nop 1
	v_cndmask_b32_e64 v75, v76, v78, s[0:1]
	v_mul_f32_e32 v76, 0x37800000, v75
	v_cndmask_b32_e32 v75, v75, v76, vcc
	v_cmp_class_f32_e32 vcc, v74, v161
	s_nop 1
	v_cndmask_b32_e32 v74, v75, v74, vcc
	v_div_scale_f32 v75, s[0:1], v74, v74, 0.5
	v_rcp_f32_e32 v76, v75
	s_nop 0
	v_fma_f32 v78, -v75, v76, 1.0
	v_fmac_f32_e32 v76, v78, v76
	v_div_scale_f32 v78, vcc, 0.5, v74, 0.5
	v_mul_f32_e32 v96, v78, v76
	v_fma_f32 v98, -v75, v96, v78
	v_fmac_f32_e32 v96, v98, v76
	v_fma_f32 v75, -v75, v96, v78
	v_div_fmas_f32 v75, v75, v76, v96
	v_div_fixup_f32 v78, v75, v74, 0.5
	v_pk_mul_f32 v[74:75], v[78:79], v[146:147] op_sel_hi:[0,1]
	v_pk_mul_f32 v[72:73], v[78:79], v[72:73] op_sel_hi:[0,1]
	s_waitcnt vmcnt(1)
	v_pk_mul_f32 v[138:139], v[72:73], v[138:139]
	v_pk_mul_f32 v[72:73], v[74:75], v[136:137]
	s_waitcnt vmcnt(0)
	v_pk_fma_f32 v[74:75], v[138:139], v[142:143], v[62:63]
	v_pk_fma_f32 v[72:73], v[72:73], v[140:141], v[60:61]
	v_and_b32_sdwa v60, v74, v162 dst_sel:DWORD dst_unused:UNUSED_PAD src0_sel:WORD_1 src1_sel:DWORD
	v_and_b32_sdwa v61, v72, v162 dst_sel:DWORD dst_unused:UNUSED_PAD src0_sel:WORD_1 src1_sel:DWORD
	v_add3_u32 v62, v72, v61, s24
	v_and_b32_sdwa v61, v75, v162 dst_sel:DWORD dst_unused:UNUSED_PAD src0_sel:WORD_1 src1_sel:DWORD
	v_and_b32_sdwa v63, v73, v162 dst_sel:DWORD dst_unused:UNUSED_PAD src0_sel:WORD_1 src1_sel:DWORD
	v_add3_u32 v61, v75, v61, s24
	v_add3_u32 v63, v73, v63, s24
	v_add3_u32 v60, v74, v60, s24
	v_and_b32_e32 v61, 0xffff0000, v61
	v_and_b32_e32 v63, 0xffff0000, v63
	v_or_b32_sdwa v61, v61, v60 dst_sel:DWORD dst_unused:UNUSED_PAD src0_sel:DWORD src1_sel:WORD_1
	v_or_b32_sdwa v60, v63, v62 dst_sel:DWORD dst_unused:UNUSED_PAD src0_sel:DWORD src1_sel:WORD_1
	buffer_store_dwordx2 v[60:61], v153, s[64:67], 0 offen nt
	v_pk_mul_f32 v[60:61], v[74:75], v[74:75]
	v_pk_mul_f32 v[62:63], v[72:73], v[72:73]
	v_mov_b32_e32 v142, v69
	v_pk_mov_b32 v[136:137], v[62:63], v[60:61] op_sel:[1,0]
	v_mov_b32_e32 v63, v61
	v_pk_add_f32 v[140:141], v[136:137], v[62:63]
	buffer_load_dwordx4 v[60:63], v152, s[12:15], s30 offen
	buffer_load_dwordx4 v[136:139], v152, s[68:71], s30 offen
	v_mov_b32_e32 v69, v70
	v_mov_b32_e32 v143, v71
	v_pk_mul_f32 v[68:69], v[78:79], v[68:69] op_sel_hi:[0,1]
	v_pk_mul_f32 v[142:143], v[78:79], v[142:143] op_sel_hi:[0,1]
	v_pk_mul_f32 v[64:65], v[78:79], v[64:65] op_sel_hi:[0,1]
	v_pk_mul_f32 v[66:67], v[78:79], v[66:67] op_sel_hi:[0,1]
	v_mov_b32_e32 v96, v99
	v_mov_b32_e32 v76, v79
	s_waitcnt vmcnt(1)
	v_pk_mul_f32 v[60:61], v[68:69], v[60:61]
	v_pk_mul_f32 v[62:63], v[142:143], v[62:63]
	s_waitcnt vmcnt(0)
	v_pk_fma_f32 v[70:71], v[60:61], v[136:137], v[56:57]
	v_pk_fma_f32 v[68:69], v[62:63], v[138:139], v[58:59]
	v_and_b32_sdwa v57, v70, v162 dst_sel:DWORD dst_unused:UNUSED_PAD src0_sel:WORD_1 src1_sel:DWORD
	v_add3_u32 v58, v70, v57, s24
	v_and_b32_sdwa v57, v69, v162 dst_sel:DWORD dst_unused:UNUSED_PAD src0_sel:WORD_1 src1_sel:DWORD
	v_and_b32_sdwa v59, v71, v162 dst_sel:DWORD dst_unused:UNUSED_PAD src0_sel:WORD_1 src1_sel:DWORD
	v_and_b32_sdwa v56, v68, v162 dst_sel:DWORD dst_unused:UNUSED_PAD src0_sel:WORD_1 src1_sel:DWORD
	v_add3_u32 v57, v69, v57, s24
	v_add3_u32 v59, v71, v59, s24
	v_add3_u32 v56, v68, v56, s24
	v_and_b32_e32 v57, 0xffff0000, v57
	v_and_b32_e32 v59, 0xffff0000, v59
	v_or_b32_sdwa v57, v57, v56 dst_sel:DWORD dst_unused:UNUSED_PAD src0_sel:DWORD src1_sel:WORD_1
	v_or_b32_sdwa v56, v59, v58 dst_sel:DWORD dst_unused:UNUSED_PAD src0_sel:DWORD src1_sel:WORD_1
	buffer_store_dwordx2 v[56:57], v153, s[64:67], s29 offen nt
	v_pk_mul_f32 v[56:57], v[70:71], v[70:71]
	v_pk_mul_f32 v[58:59], v[68:69], v[68:69]
	s_nop 0
	v_pk_mov_b32 v[60:61], v[56:57], v[58:59] op_sel:[1,0]
	v_mov_b32_e32 v57, v59
	v_pk_add_f32 v[136:137], v[60:61], v[56:57]
	buffer_load_dwordx4 v[56:59], v152, s[12:15], s33 offen
	buffer_load_dwordx4 v[60:63], v152, s[68:71], s33 offen
	s_waitcnt vmcnt(1)
	v_pk_mul_f32 v[56:57], v[64:65], v[56:57]
	v_pk_mul_f32 v[58:59], v[66:67], v[58:59]
	s_waitcnt vmcnt(0)
	v_pk_fma_f32 v[64:65], v[56:57], v[60:61], v[52:53]
	v_pk_fma_f32 v[66:67], v[58:59], v[62:63], v[54:55]
	v_and_b32_sdwa v53, v64, v162 dst_sel:DWORD dst_unused:UNUSED_PAD src0_sel:WORD_1 src1_sel:DWORD
	v_add3_u32 v54, v64, v53, s24
	v_and_b32_sdwa v53, v67, v162 dst_sel:DWORD dst_unused:UNUSED_PAD src0_sel:WORD_1 src1_sel:DWORD
	v_and_b32_sdwa v55, v65, v162 dst_sel:DWORD dst_unused:UNUSED_PAD src0_sel:WORD_1 src1_sel:DWORD
	v_and_b32_sdwa v52, v66, v162 dst_sel:DWORD dst_unused:UNUSED_PAD src0_sel:WORD_1 src1_sel:DWORD
	v_add3_u32 v53, v67, v53, s24
	v_add3_u32 v55, v65, v55, s24
	v_add3_u32 v52, v66, v52, s24
	v_and_b32_e32 v53, 0xffff0000, v53
	v_and_b32_e32 v55, 0xffff0000, v55
	v_or_b32_sdwa v53, v53, v52 dst_sel:DWORD dst_unused:UNUSED_PAD src0_sel:DWORD src1_sel:WORD_1
	v_or_b32_sdwa v52, v55, v54 dst_sel:DWORD dst_unused:UNUSED_PAD src0_sel:DWORD src1_sel:WORD_1
	buffer_store_dwordx2 v[52:53], v153, s[64:67], s30 offen nt
	buffer_load_dwordx4 v[52:55], v152, s[12:15], s53 offen
	s_nop 0
	buffer_load_dwordx4 v[56:59], v152, s[68:71], s53 offen
	v_pk_mul_f32 v[62:63], v[78:79], v[130:131] op_sel_hi:[0,1]
	v_pk_mul_f32 v[60:61], v[78:79], v[134:135] op_sel_hi:[0,1]
	s_waitcnt vmcnt(1)
	v_pk_mul_f32 v[52:53], v[62:63], v[52:53]
	v_pk_mul_f32 v[54:55], v[60:61], v[54:55]
	s_waitcnt vmcnt(0)
	v_pk_fma_f32 v[62:63], v[52:53], v[56:57], v[48:49]
	v_pk_fma_f32 v[60:61], v[54:55], v[58:59], v[50:51]
	v_and_b32_sdwa v49, v62, v162 dst_sel:DWORD dst_unused:UNUSED_PAD src0_sel:WORD_1 src1_sel:DWORD
	v_add3_u32 v50, v62, v49, s24
	v_and_b32_sdwa v49, v61, v162 dst_sel:DWORD dst_unused:UNUSED_PAD src0_sel:WORD_1 src1_sel:DWORD
	v_and_b32_sdwa v51, v63, v162 dst_sel:DWORD dst_unused:UNUSED_PAD src0_sel:WORD_1 src1_sel:DWORD
	v_and_b32_sdwa v48, v60, v162 dst_sel:DWORD dst_unused:UNUSED_PAD src0_sel:WORD_1 src1_sel:DWORD
	v_add3_u32 v49, v61, v49, s24
	v_add3_u32 v51, v63, v51, s24
	v_add3_u32 v48, v60, v48, s24
	v_and_b32_e32 v49, 0xffff0000, v49
	v_and_b32_e32 v51, 0xffff0000, v51
	v_or_b32_sdwa v49, v49, v48 dst_sel:DWORD dst_unused:UNUSED_PAD src0_sel:DWORD src1_sel:WORD_1
	v_or_b32_sdwa v48, v51, v50 dst_sel:DWORD dst_unused:UNUSED_PAD src0_sel:DWORD src1_sel:WORD_1
	buffer_store_dwordx2 v[48:49], v153, s[64:67], s31 offen nt
	v_mul_f32_e32 v48, v65, v65
	v_mul_f32_e32 v50, v62, v62
	v_pk_fma_f32 v[48:49], v[64:65], v[64:65], v[48:49] op_sel_hi:[1,1,0]
	v_mul_f32_e32 v52, v63, v63
	v_mov_b32_e32 v49, v50
	v_mul_f32_e32 v50, v67, v67
	v_pk_fma_f32 v[50:51], v[66:67], v[66:67], v[50:51] op_sel_hi:[1,1,0]
	v_mul_f32_e32 v53, v60, v60
	v_mov_b32_e32 v51, v52
	v_pk_add_f32 v[48:49], v[48:49], v[50:51]
	v_pk_add_f32 v[50:51], v[140:141], v[140:141] op_sel:[0,1] op_sel_hi:[1,0]
	v_mul_f32_e32 v54, v61, v61
	v_mov_b32_e32 v51, v53
	v_pk_add_f32 v[52:53], v[136:137], v[136:137] op_sel:[0,1] op_sel_hi:[1,0]
	v_mov_b32_e32 v56, v127
	v_mov_b32_e32 v53, v54
	v_pk_add_f32 v[50:51], v[50:51], v[52:53]
	v_mov_b32_e32 v127, v128
	v_pk_add_f32 v[130:131], v[48:49], v[50:51]
	buffer_load_dwordx4 v[48:51], v152, s[12:15], s55 offen
	buffer_load_dwordx4 v[52:55], v152, s[68:71], s55 offen
	v_mov_b32_e32 v57, v129
	v_pk_mul_f32 v[58:59], v[78:79], v[126:127] op_sel_hi:[0,1]
	v_pk_mul_f32 v[56:57], v[78:79], v[56:57] op_sel_hi:[0,1]
	s_waitcnt vmcnt(1)
	v_pk_mul_f32 v[48:49], v[58:59], v[48:49]
	v_pk_mul_f32 v[50:51], v[56:57], v[50:51]
	s_waitcnt vmcnt(0)
	v_pk_fma_f32 v[58:59], v[48:49], v[52:53], v[44:45]
	v_pk_fma_f32 v[56:57], v[50:51], v[54:55], v[46:47]
	v_and_b32_sdwa v45, v58, v162 dst_sel:DWORD dst_unused:UNUSED_PAD src0_sel:WORD_1 src1_sel:DWORD
	v_add3_u32 v46, v58, v45, s24
	v_and_b32_sdwa v45, v57, v162 dst_sel:DWORD dst_unused:UNUSED_PAD src0_sel:WORD_1 src1_sel:DWORD
	v_and_b32_sdwa v47, v59, v162 dst_sel:DWORD dst_unused:UNUSED_PAD src0_sel:WORD_1 src1_sel:DWORD
	v_and_b32_sdwa v44, v56, v162 dst_sel:DWORD dst_unused:UNUSED_PAD src0_sel:WORD_1 src1_sel:DWORD
	v_add3_u32 v45, v57, v45, s24
	v_add3_u32 v47, v59, v47, s24
	v_add3_u32 v44, v56, v44, s24
	v_and_b32_e32 v45, 0xffff0000, v45
	v_and_b32_e32 v47, 0xffff0000, v47
	v_or_b32_sdwa v45, v45, v44 dst_sel:DWORD dst_unused:UNUSED_PAD src0_sel:DWORD src1_sel:WORD_1
	v_or_b32_sdwa v44, v47, v46 dst_sel:DWORD dst_unused:UNUSED_PAD src0_sel:DWORD src1_sel:WORD_1
	buffer_store_dwordx2 v[44:45], v153, s[64:67], s33 offen nt
	v_pk_mul_f32 v[44:45], v[58:59], v[58:59]
	v_pk_mul_f32 v[46:47], v[56:57], v[56:57]
	v_mov_b32_e32 v52, v122
	v_pk_mov_b32 v[48:49], v[44:45], v[46:47] op_sel:[1,0]
	v_mov_b32_e32 v45, v47
	v_pk_add_f32 v[126:127], v[48:49], v[44:45]
	buffer_load_dwordx4 v[44:47], v152, s[12:15], s76 offen
	buffer_load_dwordx4 v[48:51], v152, s[68:71], s76 offen
	v_mov_b32_e32 v53, v124
	v_pk_mul_f32 v[52:53], v[78:79], v[52:53] op_sel_hi:[0,1]
	v_mov_b32_e32 v124, v123
	v_pk_mul_f32 v[54:55], v[78:79], v[124:125] op_sel_hi:[0,1]
	s_waitcnt vmcnt(1)
	v_pk_mul_f32 v[44:45], v[52:53], v[44:45]
	v_pk_mul_f32 v[46:47], v[54:55], v[46:47]
	s_waitcnt vmcnt(0)
	v_pk_fma_f32 v[52:53], v[44:45], v[48:49], v[40:41]
	v_pk_fma_f32 v[54:55], v[46:47], v[50:51], v[42:43]
	v_and_b32_sdwa v41, v52, v162 dst_sel:DWORD dst_unused:UNUSED_PAD src0_sel:WORD_1 src1_sel:DWORD
	v_add3_u32 v42, v52, v41, s24
	v_and_b32_sdwa v41, v55, v162 dst_sel:DWORD dst_unused:UNUSED_PAD src0_sel:WORD_1 src1_sel:DWORD
	v_and_b32_sdwa v43, v53, v162 dst_sel:DWORD dst_unused:UNUSED_PAD src0_sel:WORD_1 src1_sel:DWORD
	v_and_b32_sdwa v40, v54, v162 dst_sel:DWORD dst_unused:UNUSED_PAD src0_sel:WORD_1 src1_sel:DWORD
	v_add3_u32 v41, v55, v41, s24
	v_add3_u32 v43, v53, v43, s24
	v_add3_u32 v40, v54, v40, s24
	v_and_b32_e32 v41, 0xffff0000, v41
	v_and_b32_e32 v43, 0xffff0000, v43
	v_or_b32_sdwa v41, v41, v40 dst_sel:DWORD dst_unused:UNUSED_PAD src0_sel:DWORD src1_sel:WORD_1
	v_or_b32_sdwa v40, v43, v42 dst_sel:DWORD dst_unused:UNUSED_PAD src0_sel:DWORD src1_sel:WORD_1
	buffer_store_dwordx2 v[40:41], v153, s[64:67], s35 offen nt
	buffer_load_dwordx4 v[40:43], v152, s[12:15], s94 offen
	s_nop 0
	buffer_load_dwordx4 v[44:47], v152, s[68:71], s94 offen
	v_pk_mul_f32 v[50:51], v[78:79], v[118:119] op_sel_hi:[0,1]
	v_pk_mul_f32 v[48:49], v[78:79], v[120:121] op_sel_hi:[0,1]
	s_waitcnt vmcnt(1)
	v_pk_mul_f32 v[40:41], v[50:51], v[40:41]
	v_pk_mul_f32 v[42:43], v[48:49], v[42:43]
	s_waitcnt vmcnt(0)
	v_pk_fma_f32 v[50:51], v[40:41], v[44:45], v[36:37]
	v_pk_fma_f32 v[48:49], v[42:43], v[46:47], v[38:39]
	v_and_b32_sdwa v37, v50, v162 dst_sel:DWORD dst_unused:UNUSED_PAD src0_sel:WORD_1 src1_sel:DWORD
	v_add3_u32 v38, v50, v37, s24
	v_and_b32_sdwa v37, v49, v162 dst_sel:DWORD dst_unused:UNUSED_PAD src0_sel:WORD_1 src1_sel:DWORD
	v_and_b32_sdwa v39, v51, v162 dst_sel:DWORD dst_unused:UNUSED_PAD src0_sel:WORD_1 src1_sel:DWORD
	v_and_b32_sdwa v36, v48, v162 dst_sel:DWORD dst_unused:UNUSED_PAD src0_sel:WORD_1 src1_sel:DWORD
	v_add3_u32 v37, v49, v37, s24
	v_add3_u32 v39, v51, v39, s24
	v_add3_u32 v36, v48, v36, s24
	v_and_b32_e32 v37, 0xffff0000, v37
	v_and_b32_e32 v39, 0xffff0000, v39
	v_or_b32_sdwa v37, v37, v36 dst_sel:DWORD dst_unused:UNUSED_PAD src0_sel:DWORD src1_sel:WORD_1
	v_or_b32_sdwa v36, v39, v38 dst_sel:DWORD dst_unused:UNUSED_PAD src0_sel:DWORD src1_sel:WORD_1
	buffer_store_dwordx2 v[36:37], v153, s[64:67], s53 offen nt
	v_mul_f32_e32 v38, v50, v50
	v_pk_add_f32 v[36:37], v[130:131], v[130:131] op_sel:[0,1] op_sel_hi:[1,0]
	v_mul_f32_e32 v40, v51, v51
	v_mov_b32_e32 v37, v38
	v_pk_add_f32 v[38:39], v[126:127], v[126:127] op_sel:[0,1] op_sel_hi:[1,0]
	v_mul_f32_e32 v41, v48, v48
	v_mov_b32_e32 v39, v40
	v_pk_add_f32 v[36:37], v[36:37], v[38:39]
	v_mul_f32_e32 v38, v53, v53
	v_pk_fma_f32 v[38:39], v[52:53], v[52:53], v[38:39] op_sel_hi:[1,1,0]
	v_mul_f32_e32 v40, v55, v55
	v_mul_f32_e32 v42, v49, v49
	v_mov_b32_e32 v39, v41
	v_pk_fma_f32 v[40:41], v[54:55], v[54:55], v[40:41] op_sel_hi:[1,1,0]
	v_pk_mul_f32 v[46:47], v[78:79], v[112:113] op_sel_hi:[0,1]
	v_mov_b32_e32 v41, v42
	v_pk_add_f32 v[38:39], v[38:39], v[40:41]
	v_pk_mul_f32 v[44:45], v[78:79], v[116:117] op_sel_hi:[0,1]
	v_pk_add_f32 v[118:119], v[36:37], v[38:39]
	buffer_load_dwordx4 v[36:39], v152, s[12:15], s78 offen
	buffer_load_dwordx4 v[40:43], v152, s[68:71], s78 offen
	s_waitcnt vmcnt(1)
	v_pk_mul_f32 v[36:37], v[46:47], v[36:37]
	v_pk_mul_f32 v[38:39], v[44:45], v[38:39]
	s_waitcnt vmcnt(0)
	v_pk_fma_f32 v[46:47], v[36:37], v[40:41], v[32:33]
	v_pk_fma_f32 v[44:45], v[38:39], v[42:43], v[34:35]
	v_and_b32_sdwa v33, v46, v162 dst_sel:DWORD dst_unused:UNUSED_PAD src0_sel:WORD_1 src1_sel:DWORD
	v_add3_u32 v34, v46, v33, s24
	v_and_b32_sdwa v33, v45, v162 dst_sel:DWORD dst_unused:UNUSED_PAD src0_sel:WORD_1 src1_sel:DWORD
	v_and_b32_sdwa v35, v47, v162 dst_sel:DWORD dst_unused:UNUSED_PAD src0_sel:WORD_1 src1_sel:DWORD
	v_and_b32_sdwa v32, v44, v162 dst_sel:DWORD dst_unused:UNUSED_PAD src0_sel:WORD_1 src1_sel:DWORD
	v_add3_u32 v33, v45, v33, s24
	v_add3_u32 v35, v47, v35, s24
	v_add3_u32 v32, v44, v32, s24
	v_and_b32_e32 v33, 0xffff0000, v33
	v_and_b32_e32 v35, 0xffff0000, v35
	v_or_b32_sdwa v33, v33, v32 dst_sel:DWORD dst_unused:UNUSED_PAD src0_sel:DWORD src1_sel:WORD_1
	v_or_b32_sdwa v32, v35, v34 dst_sel:DWORD dst_unused:UNUSED_PAD src0_sel:DWORD src1_sel:WORD_1
	buffer_store_dwordx2 v[32:33], v153, s[64:67], s54 offen nt
	v_pk_mul_f32 v[32:33], v[46:47], v[46:47]
	v_pk_mul_f32 v[34:35], v[44:45], v[44:45]
	v_mov_b32_e32 v40, v108
	v_pk_mov_b32 v[36:37], v[32:33], v[34:35] op_sel:[1,0]
	v_mov_b32_e32 v33, v35
	v_pk_add_f32 v[112:113], v[36:37], v[32:33]
	buffer_load_dwordx4 v[32:35], v152, s[12:15], s10 offen
	buffer_load_dwordx4 v[36:39], v152, s[68:71], s10 offen
	v_mov_b32_e32 v41, v110
	v_pk_mul_f32 v[40:41], v[78:79], v[40:41] op_sel_hi:[0,1]
	v_mov_b32_e32 v110, v109
	v_pk_mul_f32 v[42:43], v[78:79], v[110:111] op_sel_hi:[0,1]
	s_waitcnt vmcnt(1)
	v_pk_mul_f32 v[32:33], v[40:41], v[32:33]
	v_pk_mul_f32 v[34:35], v[42:43], v[34:35]
	s_waitcnt vmcnt(0)
	v_pk_fma_f32 v[40:41], v[32:33], v[36:37], v[28:29]
	v_pk_fma_f32 v[42:43], v[34:35], v[38:39], v[30:31]
	v_and_b32_sdwa v29, v40, v162 dst_sel:DWORD dst_unused:UNUSED_PAD src0_sel:WORD_1 src1_sel:DWORD
	v_add3_u32 v30, v40, v29, s24
	v_and_b32_sdwa v29, v43, v162 dst_sel:DWORD dst_unused:UNUSED_PAD src0_sel:WORD_1 src1_sel:DWORD
	v_and_b32_sdwa v31, v41, v162 dst_sel:DWORD dst_unused:UNUSED_PAD src0_sel:WORD_1 src1_sel:DWORD
	v_and_b32_sdwa v28, v42, v162 dst_sel:DWORD dst_unused:UNUSED_PAD src0_sel:WORD_1 src1_sel:DWORD
	v_add3_u32 v29, v43, v29, s24
	v_add3_u32 v31, v41, v31, s24
	v_add3_u32 v28, v42, v28, s24
	v_and_b32_e32 v29, 0xffff0000, v29
	v_and_b32_e32 v31, 0xffff0000, v31
	v_or_b32_sdwa v29, v29, v28 dst_sel:DWORD dst_unused:UNUSED_PAD src0_sel:DWORD src1_sel:WORD_1
	v_or_b32_sdwa v28, v31, v30 dst_sel:DWORD dst_unused:UNUSED_PAD src0_sel:DWORD src1_sel:WORD_1
	buffer_store_dwordx2 v[28:29], v153, s[64:67], s55 offen nt
	buffer_load_dwordx4 v[28:31], v152, s[12:15], s88 offen
	s_nop 0
	buffer_load_dwordx4 v[32:35], v152, s[68:71], s88 offen
	v_mov_b32_e32 v36, v105
	v_mov_b32_e32 v105, v106
	v_mov_b32_e32 v37, v107
	v_pk_mul_f32 v[38:39], v[78:79], v[104:105] op_sel_hi:[0,1]
	v_pk_mul_f32 v[36:37], v[78:79], v[36:37] op_sel_hi:[0,1]
	s_waitcnt vmcnt(1)
	v_pk_mul_f32 v[28:29], v[38:39], v[28:29]
	v_pk_mul_f32 v[30:31], v[36:37], v[30:31]
	s_waitcnt vmcnt(0)
	v_pk_fma_f32 v[38:39], v[28:29], v[32:33], v[24:25]
	v_pk_fma_f32 v[36:37], v[30:31], v[34:35], v[26:27]
	v_and_b32_sdwa v25, v38, v162 dst_sel:DWORD dst_unused:UNUSED_PAD src0_sel:WORD_1 src1_sel:DWORD
	v_add3_u32 v26, v38, v25, s24
	v_and_b32_sdwa v25, v37, v162 dst_sel:DWORD dst_unused:UNUSED_PAD src0_sel:WORD_1 src1_sel:DWORD
	v_and_b32_sdwa v27, v39, v162 dst_sel:DWORD dst_unused:UNUSED_PAD src0_sel:WORD_1 src1_sel:DWORD
	v_and_b32_sdwa v24, v36, v162 dst_sel:DWORD dst_unused:UNUSED_PAD src0_sel:WORD_1 src1_sel:DWORD
	v_add3_u32 v25, v37, v25, s24
	v_add3_u32 v27, v39, v27, s24
	v_add3_u32 v24, v36, v24, s24
	v_and_b32_e32 v25, 0xffff0000, v25
	v_and_b32_e32 v27, 0xffff0000, v27
	v_or_b32_sdwa v25, v25, v24 dst_sel:DWORD dst_unused:UNUSED_PAD src0_sel:DWORD src1_sel:WORD_1
	v_or_b32_sdwa v24, v27, v26 dst_sel:DWORD dst_unused:UNUSED_PAD src0_sel:DWORD src1_sel:WORD_1
	buffer_store_dwordx2 v[24:25], v153, s[64:67], s73 offen nt
	v_mul_f32_e32 v26, v38, v38
	v_pk_add_f32 v[24:25], v[118:119], v[118:119] op_sel:[0,1] op_sel_hi:[1,0]
	v_mul_f32_e32 v28, v39, v39
	v_mov_b32_e32 v25, v26
	v_pk_add_f32 v[26:27], v[112:113], v[112:113] op_sel:[0,1] op_sel_hi:[1,0]
	v_mul_f32_e32 v29, v36, v36
	v_mov_b32_e32 v27, v28
	v_pk_add_f32 v[24:25], v[24:25], v[26:27]
	v_mul_f32_e32 v26, v41, v41
	v_pk_fma_f32 v[26:27], v[40:41], v[40:41], v[26:27] op_sel_hi:[1,1,0]
	v_mul_f32_e32 v28, v43, v43
	v_mul_f32_e32 v30, v37, v37
	v_mov_b32_e32 v27, v29
	v_pk_fma_f32 v[28:29], v[42:43], v[42:43], v[28:29] op_sel_hi:[1,1,0]
	v_pk_mul_f32 v[34:35], v[78:79], v[100:101] op_sel_hi:[0,1]
	v_mov_b32_e32 v29, v30
	v_pk_add_f32 v[26:27], v[26:27], v[28:29]
	v_pk_mul_f32 v[32:33], v[78:79], v[102:103] op_sel_hi:[0,1]
	v_pk_add_f32 v[104:105], v[24:25], v[26:27]
	buffer_load_dwordx4 v[24:27], v152, s[12:15], s89 offen
	buffer_load_dwordx4 v[28:31], v152, s[68:71], s89 offen
	s_waitcnt vmcnt(1)
	v_pk_mul_f32 v[24:25], v[34:35], v[24:25]
	v_pk_mul_f32 v[26:27], v[32:33], v[26:27]
	s_waitcnt vmcnt(0)
	v_pk_fma_f32 v[34:35], v[24:25], v[28:29], v[20:21]
	v_pk_fma_f32 v[32:33], v[26:27], v[30:31], v[22:23]
	v_and_b32_sdwa v21, v34, v162 dst_sel:DWORD dst_unused:UNUSED_PAD src0_sel:WORD_1 src1_sel:DWORD
	v_add3_u32 v22, v34, v21, s24
	v_and_b32_sdwa v21, v33, v162 dst_sel:DWORD dst_unused:UNUSED_PAD src0_sel:WORD_1 src1_sel:DWORD
	v_and_b32_sdwa v23, v35, v162 dst_sel:DWORD dst_unused:UNUSED_PAD src0_sel:WORD_1 src1_sel:DWORD
	v_and_b32_sdwa v20, v32, v162 dst_sel:DWORD dst_unused:UNUSED_PAD src0_sel:WORD_1 src1_sel:DWORD
	v_add3_u32 v21, v33, v21, s24
	v_add3_u32 v23, v35, v23, s24
	v_add3_u32 v20, v32, v20, s24
	v_and_b32_e32 v21, 0xffff0000, v21
	v_and_b32_e32 v23, 0xffff0000, v23
	v_or_b32_sdwa v21, v21, v20 dst_sel:DWORD dst_unused:UNUSED_PAD src0_sel:DWORD src1_sel:WORD_1
	v_or_b32_sdwa v20, v23, v22 dst_sel:DWORD dst_unused:UNUSED_PAD src0_sel:DWORD src1_sel:WORD_1
	buffer_store_dwordx2 v[20:21], v153, s[64:67], s76 offen nt
	v_pk_mul_f32 v[20:21], v[34:35], v[34:35]
	v_pk_mul_f32 v[22:23], v[32:33], v[32:33]
	v_pk_mul_f32 v[28:29], v[78:79], v[96:97] op_sel_hi:[0,1]
	v_pk_mov_b32 v[24:25], v[20:21], v[22:23] op_sel:[1,0]
	v_mov_b32_e32 v21, v23
	v_pk_add_f32 v[100:101], v[24:25], v[20:21]
	buffer_load_dwordx4 v[20:23], v152, s[12:15], s82 offen
	buffer_load_dwordx4 v[24:27], v152, s[68:71], s82 offen
	v_pk_mul_f32 v[30:31], v[78:79], v[94:95] op_sel_hi:[0,1]
	s_waitcnt vmcnt(1)
	v_pk_mul_f32 v[20:21], v[28:29], v[20:21]
	v_pk_mul_f32 v[22:23], v[30:31], v[22:23]
	s_waitcnt vmcnt(0)
	v_pk_fma_f32 v[28:29], v[20:21], v[24:25], v[16:17]
	v_pk_fma_f32 v[30:31], v[22:23], v[26:27], v[18:19]
	v_and_b32_sdwa v17, v28, v162 dst_sel:DWORD dst_unused:UNUSED_PAD src0_sel:WORD_1 src1_sel:DWORD
	v_add3_u32 v18, v28, v17, s24
	v_and_b32_sdwa v17, v31, v162 dst_sel:DWORD dst_unused:UNUSED_PAD src0_sel:WORD_1 src1_sel:DWORD
	v_and_b32_sdwa v19, v29, v162 dst_sel:DWORD dst_unused:UNUSED_PAD src0_sel:WORD_1 src1_sel:DWORD
	v_and_b32_sdwa v16, v30, v162 dst_sel:DWORD dst_unused:UNUSED_PAD src0_sel:WORD_1 src1_sel:DWORD
	v_add3_u32 v17, v31, v17, s24
	v_add3_u32 v19, v29, v19, s24
	v_add3_u32 v16, v30, v16, s24
	v_and_b32_e32 v17, 0xffff0000, v17
	v_and_b32_e32 v19, 0xffff0000, v19
	v_or_b32_sdwa v17, v17, v16 dst_sel:DWORD dst_unused:UNUSED_PAD src0_sel:DWORD src1_sel:WORD_1
	v_or_b32_sdwa v16, v19, v18 dst_sel:DWORD dst_unused:UNUSED_PAD src0_sel:DWORD src1_sel:WORD_1
	buffer_store_dwordx2 v[16:17], v153, s[64:67], s77 offen nt
	buffer_load_dwordx4 v[16:19], v152, s[12:15], s83 offen
	s_nop 0
	buffer_load_dwordx4 v[20:23], v152, s[68:71], s83 offen
	v_mov_b32_e32 v24, v91
	v_mov_b32_e32 v91, v92
	v_mov_b32_e32 v25, v93
	v_pk_mul_f32 v[26:27], v[78:79], v[90:91] op_sel_hi:[0,1]
	v_pk_mul_f32 v[24:25], v[78:79], v[24:25] op_sel_hi:[0,1]
	s_waitcnt vmcnt(1)
	v_pk_mul_f32 v[16:17], v[26:27], v[16:17]
	v_pk_mul_f32 v[18:19], v[24:25], v[18:19]
	s_waitcnt vmcnt(0)
	v_pk_fma_f32 v[26:27], v[16:17], v[20:21], v[12:13]
	v_pk_fma_f32 v[24:25], v[18:19], v[22:23], v[14:15]
	v_and_b32_sdwa v13, v26, v162 dst_sel:DWORD dst_unused:UNUSED_PAD src0_sel:WORD_1 src1_sel:DWORD
	v_add3_u32 v14, v26, v13, s24
	v_and_b32_sdwa v13, v25, v162 dst_sel:DWORD dst_unused:UNUSED_PAD src0_sel:WORD_1 src1_sel:DWORD
	v_and_b32_sdwa v15, v27, v162 dst_sel:DWORD dst_unused:UNUSED_PAD src0_sel:WORD_1 src1_sel:DWORD
	v_and_b32_sdwa v12, v24, v162 dst_sel:DWORD dst_unused:UNUSED_PAD src0_sel:WORD_1 src1_sel:DWORD
	v_add3_u32 v13, v25, v13, s24
	v_add3_u32 v15, v27, v15, s24
	v_add3_u32 v12, v24, v12, s24
	v_and_b32_e32 v13, 0xffff0000, v13
	v_and_b32_e32 v15, 0xffff0000, v15
	v_or_b32_sdwa v13, v13, v12 dst_sel:DWORD dst_unused:UNUSED_PAD src0_sel:DWORD src1_sel:WORD_1
	v_or_b32_sdwa v12, v15, v14 dst_sel:DWORD dst_unused:UNUSED_PAD src0_sel:DWORD src1_sel:WORD_1
	buffer_store_dwordx2 v[12:13], v153, s[64:67], s94 offen nt
	v_mul_f32_e32 v14, v26, v26
	v_pk_add_f32 v[12:13], v[104:105], v[104:105] op_sel:[0,1] op_sel_hi:[1,0]
	v_mul_f32_e32 v16, v27, v27
	v_mov_b32_e32 v13, v14
	v_pk_add_f32 v[14:15], v[100:101], v[100:101] op_sel:[0,1] op_sel_hi:[1,0]
	v_mul_f32_e32 v17, v24, v24
	v_mov_b32_e32 v15, v16
	v_pk_add_f32 v[12:13], v[12:13], v[14:15]
	v_mul_f32_e32 v14, v29, v29
	v_pk_fma_f32 v[14:15], v[28:29], v[28:29], v[14:15] op_sel_hi:[1,1,0]
	v_mul_f32_e32 v16, v31, v31
	v_mul_f32_e32 v18, v25, v25
	v_mov_b32_e32 v15, v17
	v_pk_fma_f32 v[16:17], v[30:31], v[30:31], v[16:17] op_sel_hi:[1,1,0]
	v_mov_b32_e32 v20, v87
	v_mov_b32_e32 v17, v18
	v_pk_add_f32 v[14:15], v[14:15], v[16:17]
	v_mov_b32_e32 v87, v88
	v_pk_add_f32 v[90:91], v[12:13], v[14:15]
	buffer_load_dwordx4 v[12:15], v152, s[12:15], s96 offen
	buffer_load_dwordx4 v[16:19], v152, s[68:71], s96 offen
	v_mov_b32_e32 v21, v89
	v_pk_mul_f32 v[22:23], v[78:79], v[86:87] op_sel_hi:[0,1]
	v_pk_mul_f32 v[20:21], v[78:79], v[20:21] op_sel_hi:[0,1]
	s_waitcnt vmcnt(1)
	v_pk_mul_f32 v[12:13], v[22:23], v[12:13]
	v_pk_mul_f32 v[14:15], v[20:21], v[14:15]
	s_waitcnt vmcnt(0)
	v_pk_fma_f32 v[22:23], v[12:13], v[16:17], v[8:9]
	v_pk_fma_f32 v[20:21], v[14:15], v[18:19], v[10:11]
	v_and_b32_sdwa v9, v22, v162 dst_sel:DWORD dst_unused:UNUSED_PAD src0_sel:WORD_1 src1_sel:DWORD
	v_add3_u32 v10, v22, v9, s24
	v_and_b32_sdwa v9, v21, v162 dst_sel:DWORD dst_unused:UNUSED_PAD src0_sel:WORD_1 src1_sel:DWORD
	v_and_b32_sdwa v11, v23, v162 dst_sel:DWORD dst_unused:UNUSED_PAD src0_sel:WORD_1 src1_sel:DWORD
	v_and_b32_sdwa v8, v20, v162 dst_sel:DWORD dst_unused:UNUSED_PAD src0_sel:WORD_1 src1_sel:DWORD
	v_add3_u32 v9, v21, v9, s24
	v_add3_u32 v11, v23, v11, s24
	v_add3_u32 v8, v20, v8, s24
	v_and_b32_e32 v9, 0xffff0000, v9
	v_and_b32_e32 v11, 0xffff0000, v11
	v_or_b32_sdwa v9, v9, v8 dst_sel:DWORD dst_unused:UNUSED_PAD src0_sel:DWORD src1_sel:WORD_1
	v_or_b32_sdwa v8, v11, v10 dst_sel:DWORD dst_unused:UNUSED_PAD src0_sel:DWORD src1_sel:WORD_1
	buffer_store_dwordx2 v[8:9], v153, s[64:67], s95 offen nt
	v_pk_mul_f32 v[8:9], v[22:23], v[22:23]
	v_pk_mul_f32 v[10:11], v[20:21], v[20:21]
	v_pk_mul_f32 v[16:17], v[78:79], v[82:83] op_sel_hi:[0,1]
	v_pk_mov_b32 v[12:13], v[8:9], v[10:11] op_sel:[1,0]
	v_mov_b32_e32 v9, v11
	v_pk_add_f32 v[86:87], v[12:13], v[8:9]
	buffer_load_dwordx4 v[8:11], v152, s[12:15], s97 offen
	buffer_load_dwordx4 v[12:15], v152, s[68:71], s97 offen
	v_pk_mul_f32 v[18:19], v[78:79], v[84:85] op_sel_hi:[0,1]
	s_waitcnt vmcnt(1)
	v_pk_mul_f32 v[8:9], v[16:17], v[8:9]
	v_pk_mul_f32 v[10:11], v[18:19], v[10:11]
	s_waitcnt vmcnt(0)
	v_pk_fma_f32 v[16:17], v[8:9], v[12:13], v[4:5]
	v_pk_fma_f32 v[18:19], v[10:11], v[14:15], v[6:7]
	v_and_b32_sdwa v5, v16, v162 dst_sel:DWORD dst_unused:UNUSED_PAD src0_sel:WORD_1 src1_sel:DWORD
	v_add3_u32 v6, v16, v5, s24
	v_and_b32_sdwa v5, v19, v162 dst_sel:DWORD dst_unused:UNUSED_PAD src0_sel:WORD_1 src1_sel:DWORD
	v_and_b32_sdwa v7, v17, v162 dst_sel:DWORD dst_unused:UNUSED_PAD src0_sel:WORD_1 src1_sel:DWORD
	v_and_b32_sdwa v4, v18, v162 dst_sel:DWORD dst_unused:UNUSED_PAD src0_sel:WORD_1 src1_sel:DWORD
	v_add3_u32 v5, v19, v5, s24
	v_add3_u32 v7, v17, v7, s24
	v_add3_u32 v4, v18, v4, s24
	v_and_b32_e32 v5, 0xffff0000, v5
	v_and_b32_e32 v7, 0xffff0000, v7
	v_or_b32_sdwa v5, v5, v4 dst_sel:DWORD dst_unused:UNUSED_PAD src0_sel:DWORD src1_sel:WORD_1
	v_or_b32_sdwa v4, v7, v6 dst_sel:DWORD dst_unused:UNUSED_PAD src0_sel:DWORD src1_sel:WORD_1
	buffer_store_dwordx2 v[4:5], v153, s[64:67], s78 offen nt
	buffer_load_dwordx4 v[4:7], v152, s[12:15], s81 offen
	s_nop 0
	buffer_load_dwordx4 v[8:11], v152, s[68:71], s81 offen
	v_pk_mul_f32 v[14:15], v[78:79], v[76:77] op_sel_hi:[0,1]
	v_pk_mul_f32 v[12:13], v[78:79], v[80:81] op_sel_hi:[0,1]
	s_waitcnt vmcnt(1)
	v_pk_mul_f32 v[4:5], v[14:15], v[4:5]
	v_pk_mul_f32 v[6:7], v[12:13], v[6:7]
	s_waitcnt vmcnt(0)
	v_pk_fma_f32 v[14:15], v[4:5], v[8:9], v[0:1]
	v_pk_fma_f32 v[12:13], v[6:7], v[10:11], v[2:3]
	v_and_b32_sdwa v1, v14, v162 dst_sel:DWORD dst_unused:UNUSED_PAD src0_sel:WORD_1 src1_sel:DWORD
	v_add3_u32 v2, v14, v1, s24
	v_and_b32_sdwa v1, v13, v162 dst_sel:DWORD dst_unused:UNUSED_PAD src0_sel:WORD_1 src1_sel:DWORD
	v_and_b32_sdwa v3, v15, v162 dst_sel:DWORD dst_unused:UNUSED_PAD src0_sel:WORD_1 src1_sel:DWORD
	v_and_b32_sdwa v0, v12, v162 dst_sel:DWORD dst_unused:UNUSED_PAD src0_sel:WORD_1 src1_sel:DWORD
	v_add3_u32 v1, v13, v1, s24
	v_add3_u32 v3, v15, v3, s24
	v_add3_u32 v0, v12, v0, s24
	v_and_b32_e32 v1, 0xffff0000, v1
	v_and_b32_e32 v3, 0xffff0000, v3
	v_or_b32_sdwa v1, v1, v0 dst_sel:DWORD dst_unused:UNUSED_PAD src0_sel:DWORD src1_sel:WORD_1
	v_or_b32_sdwa v0, v3, v2 dst_sel:DWORD dst_unused:UNUSED_PAD src0_sel:DWORD src1_sel:WORD_1
	buffer_store_dwordx2 v[0:1], v153, s[64:67], s79 offen nt
	v_mul_f32_e32 v2, v14, v14
	v_pk_add_f32 v[0:1], v[90:91], v[90:91] op_sel:[0,1] op_sel_hi:[1,0]
	v_mul_f32_e32 v4, v15, v15
	v_mov_b32_e32 v1, v2
	v_pk_add_f32 v[2:3], v[86:87], v[86:87] op_sel:[0,1] op_sel_hi:[1,0]
	v_mul_f32_e32 v5, v12, v12
	v_mov_b32_e32 v3, v4
	v_pk_add_f32 v[0:1], v[0:1], v[2:3]
	v_mul_f32_e32 v2, v17, v17
	v_pk_fma_f32 v[2:3], v[16:17], v[16:17], v[2:3] op_sel_hi:[1,1,0]
	v_mul_f32_e32 v4, v19, v19
	v_mul_f32_e32 v6, v13, v13
	v_mov_b32_e32 v3, v5
	v_pk_fma_f32 v[4:5], v[18:19], v[18:19], v[4:5] op_sel_hi:[1,1,0]
	s_nop 0
	v_mov_b32_e32 v5, v6
	v_pk_add_f32 v[2:3], v[2:3], v[4:5]
	s_nop 0
	v_pk_add_f32 v[0:1], v[0:1], v[2:3]
	s_nop 0
	v_add_f32_e32 v0, v0, v1
	ds_bpermute_b32 v1, v154, v0
	s_waitcnt lgkmcnt(0)
	v_add_f32_e32 v0, v0, v1
	ds_bpermute_b32 v1, v155, v0
	s_waitcnt lgkmcnt(0)
	v_add_f32_e32 v0, v0, v1
	ds_bpermute_b32 v1, v156, v0
	s_waitcnt lgkmcnt(0)
	v_add_f32_e32 v0, v0, v1
	ds_bpermute_b32 v1, v157, v0
	s_waitcnt lgkmcnt(0)
	v_add_f32_e32 v0, v0, v1
	ds_bpermute_b32 v1, v158, v0
	s_waitcnt lgkmcnt(0)
	v_add_f32_e32 v0, v0, v1
	ds_bpermute_b32 v1, v159, v0
	s_waitcnt lgkmcnt(0)
	v_add_f32_e32 v0, v0, v1
	v_fmamk_f32 v0, v0, 0x39800000, v160
	v_cmp_gt_f32_e32 vcc, s7, v0
	v_mul_f32_e32 v1, 0x4f800000, v0
	s_mov_b32 s7, s15
	v_cndmask_b32_e32 v0, v0, v1, vcc
	v_sqrt_f32_e32 v1, v0
	s_nop 0
	v_add_u32_e32 v2, -1, v1
	v_fma_f32 v3, -v2, v1, v0
	v_cmp_ge_f32_e64 s[0:1], 0, v3
	v_add_u32_e32 v3, 1, v1
	s_nop 0
	v_cndmask_b32_e64 v2, v1, v2, s[0:1]
	v_fma_f32 v1, -v3, v1, v0
	v_cmp_lt_f32_e64 s[0:1], 0, v1
	s_nop 1
	v_cndmask_b32_e64 v1, v2, v3, s[0:1]
	v_mul_f32_e32 v2, 0x37800000, v1
	v_cndmask_b32_e32 v1, v1, v2, vcc
	v_cmp_class_f32_e32 vcc, v0, v161
	s_nop 1
	v_cndmask_b32_e32 v0, v1, v0, vcc
	v_div_scale_f32 v1, s[0:1], v0, v0, 1.0
	v_rcp_f32_e32 v2, v1
	s_addc_u32 s0, s44, s37
	s_and_b32 s9, s0, 0xffff
	s_add_i32 s25, s25, s72
	v_fma_f32 v3, -v1, v2, 1.0
	v_fmac_f32_e32 v2, v3, v2
	v_div_scale_f32 v3, vcc, 1.0, v0, 1.0
	v_mul_f32_e32 v4, v3, v2
	v_fma_f32 v5, -v1, v4, v3
	v_fmac_f32_e32 v4, v5, v2
	v_fma_f32 v1, -v1, v4, v3
	v_div_fmas_f32 v1, v1, v2, v4
	v_div_fixup_f32 v76, v1, v0, 1.0
	buffer_load_dwordx4 v[0:3], v152, s[4:7], 0 offen
	buffer_load_dwordx4 v[4:7], v152, s[60:63], 0 offen
	buffer_load_dwordx4 v[8:11], v152, s[56:59], 0 offen
	v_pk_mul_f32 v[72:73], v[72:73], v[76:77] op_sel_hi:[1,0]
	v_pk_mul_f32 v[74:75], v[74:75], v[76:77] op_sel_hi:[1,0]
	v_pk_mul_f32 v[70:71], v[70:71], v[76:77] op_sel_hi:[1,0]
	v_pk_mul_f32 v[68:69], v[68:69], v[76:77] op_sel_hi:[1,0]
	v_pk_mul_f32 v[64:65], v[64:65], v[76:77] op_sel_hi:[1,0]
	v_pk_mul_f32 v[66:67], v[66:67], v[76:77] op_sel_hi:[1,0]
	v_pk_mul_f32 v[62:63], v[62:63], v[76:77] op_sel_hi:[1,0]
	v_pk_mul_f32 v[60:61], v[60:61], v[76:77] op_sel_hi:[1,0]
	v_pk_mul_f32 v[58:59], v[58:59], v[76:77] op_sel_hi:[1,0]
	v_pk_mul_f32 v[56:57], v[56:57], v[76:77] op_sel_hi:[1,0]
	v_pk_mul_f32 v[52:53], v[52:53], v[76:77] op_sel_hi:[1,0]
	v_pk_mul_f32 v[54:55], v[54:55], v[76:77] op_sel_hi:[1,0]
	v_pk_mul_f32 v[50:51], v[50:51], v[76:77] op_sel_hi:[1,0]
	v_pk_mul_f32 v[48:49], v[48:49], v[76:77] op_sel_hi:[1,0]
	v_pk_mul_f32 v[46:47], v[46:47], v[76:77] op_sel_hi:[1,0]
	v_pk_mul_f32 v[44:45], v[44:45], v[76:77] op_sel_hi:[1,0]
	v_pk_mul_f32 v[40:41], v[40:41], v[76:77] op_sel_hi:[1,0]
	v_pk_mul_f32 v[42:43], v[42:43], v[76:77] op_sel_hi:[1,0]
	v_pk_mul_f32 v[38:39], v[38:39], v[76:77] op_sel_hi:[1,0]
	v_pk_mul_f32 v[36:37], v[36:37], v[76:77] op_sel_hi:[1,0]
	v_pk_mul_f32 v[34:35], v[34:35], v[76:77] op_sel_hi:[1,0]
	v_pk_mul_f32 v[32:33], v[32:33], v[76:77] op_sel_hi:[1,0]
	v_pk_mul_f32 v[28:29], v[28:29], v[76:77] op_sel_hi:[1,0]
	v_pk_mul_f32 v[30:31], v[30:31], v[76:77] op_sel_hi:[1,0]
	v_pk_mul_f32 v[26:27], v[26:27], v[76:77] op_sel_hi:[1,0]
	v_pk_mul_f32 v[24:25], v[24:25], v[76:77] op_sel_hi:[1,0]
	v_pk_mul_f32 v[22:23], v[22:23], v[76:77] op_sel_hi:[1,0]
	v_pk_mul_f32 v[20:21], v[20:21], v[76:77] op_sel_hi:[1,0]
	v_pk_mul_f32 v[16:17], v[16:17], v[76:77] op_sel_hi:[1,0]
	v_pk_mul_f32 v[18:19], v[18:19], v[76:77] op_sel_hi:[1,0]
	v_pk_mul_f32 v[14:15], v[14:15], v[76:77] op_sel_hi:[1,0]
	v_pk_mul_f32 v[12:13], v[12:13], v[76:77] op_sel_hi:[1,0]
	s_add_u32 s36, s36, s40
	s_addc_u32 s37, s37, s41
	s_add_u32 s26, s26, s92
	s_addc_u32 s27, s27, s93
	s_cmpk_lt_i32 s25, 0x2000
	s_waitcnt vmcnt(2)
	v_pk_mul_f32 v[0:1], v[72:73], v[0:1]
	v_pk_mul_f32 v[2:3], v[74:75], v[2:3]
	s_waitcnt vmcnt(0)
	v_pk_add_f32 v[8:9], v[8:9], 1.0 op_sel_hi:[1,0]
	v_pk_add_f32 v[10:11], v[10:11], 1.0 op_sel_hi:[1,0]
	v_pk_fma_f32 v[0:1], v[8:9], v[0:1], v[4:5]
	v_pk_fma_f32 v[2:3], v[10:11], v[2:3], v[6:7]
	v_bfe_u32 v4, v0, 16, 1
	v_add3_u32 v0, v0, v4, s24
	v_bfe_u32 v4, v1, 16, 1
	v_lshrrev_b32_e32 v0, 16, v0
	v_add3_u32 v1, v1, v4, s24
	v_and_or_b32 v0, v1, s28, v0
	v_bfe_u32 v1, v2, 16, 1
	v_add3_u32 v1, v2, v1, s24
	v_bfe_u32 v2, v3, 16, 1
	v_lshrrev_b32_e32 v1, 16, v1
	v_add3_u32 v2, v3, v2, s24
	v_and_or_b32 v1, v2, s28, v1
	buffer_store_dwordx2 v[0:1], v153, s[8:11], 0 offen
	buffer_load_dwordx4 v[0:3], v152, s[4:7], s30 offen
	s_nop 0
	buffer_load_dwordx4 v[4:7], v152, s[60:63], s30 offen
	buffer_load_dwordx4 v[8:11], v152, s[56:59], s30 offen
	s_waitcnt vmcnt(2)
	v_pk_mul_f32 v[0:1], v[70:71], v[0:1]
	v_pk_mul_f32 v[2:3], v[68:69], v[2:3]
	s_waitcnt vmcnt(0)
	v_pk_add_f32 v[8:9], v[8:9], 1.0 op_sel_hi:[1,0]
	v_pk_add_f32 v[10:11], v[10:11], 1.0 op_sel_hi:[1,0]
	v_pk_fma_f32 v[0:1], v[8:9], v[0:1], v[4:5]
	v_pk_fma_f32 v[2:3], v[10:11], v[2:3], v[6:7]
	v_bfe_u32 v4, v0, 16, 1
	v_add3_u32 v0, v0, v4, s24
	v_bfe_u32 v4, v1, 16, 1
	v_lshrrev_b32_e32 v0, 16, v0
	v_add3_u32 v1, v1, v4, s24
	v_and_or_b32 v0, v1, s28, v0
	v_bfe_u32 v1, v2, 16, 1
	v_add3_u32 v1, v2, v1, s24
	v_bfe_u32 v2, v3, 16, 1
	v_lshrrev_b32_e32 v1, 16, v1
	v_add3_u32 v2, v3, v2, s24
	v_and_or_b32 v1, v2, s28, v1
	buffer_store_dwordx2 v[0:1], v153, s[8:11], s29 offen
	buffer_load_dwordx4 v[0:3], v152, s[4:7], s33 offen
	s_nop 0
	buffer_load_dwordx4 v[4:7], v152, s[60:63], s33 offen
	buffer_load_dwordx4 v[8:11], v152, s[56:59], s33 offen
	s_waitcnt vmcnt(2)
	v_pk_mul_f32 v[0:1], v[64:65], v[0:1]
	v_pk_mul_f32 v[2:3], v[66:67], v[2:3]
	s_waitcnt vmcnt(0)
	v_pk_add_f32 v[8:9], v[8:9], 1.0 op_sel_hi:[1,0]
	v_pk_add_f32 v[10:11], v[10:11], 1.0 op_sel_hi:[1,0]
	v_pk_fma_f32 v[0:1], v[8:9], v[0:1], v[4:5]
	v_pk_fma_f32 v[2:3], v[10:11], v[2:3], v[6:7]
	v_bfe_u32 v4, v0, 16, 1
	v_add3_u32 v0, v0, v4, s24
	v_bfe_u32 v4, v1, 16, 1
	v_lshrrev_b32_e32 v0, 16, v0
	v_add3_u32 v1, v1, v4, s24
	v_and_or_b32 v0, v1, s28, v0
	v_bfe_u32 v1, v2, 16, 1
	v_add3_u32 v1, v2, v1, s24
	v_bfe_u32 v2, v3, 16, 1
	v_lshrrev_b32_e32 v1, 16, v1
	v_add3_u32 v2, v3, v2, s24
	v_and_or_b32 v1, v2, s28, v1
	buffer_store_dwordx2 v[0:1], v153, s[8:11], s30 offen
	buffer_load_dwordx4 v[0:3], v152, s[4:7], s53 offen
	s_nop 0
	buffer_load_dwordx4 v[4:7], v152, s[60:63], s53 offen
	buffer_load_dwordx4 v[8:11], v152, s[56:59], s53 offen
	s_waitcnt vmcnt(2)
	v_pk_mul_f32 v[0:1], v[62:63], v[0:1]
	v_pk_mul_f32 v[2:3], v[60:61], v[2:3]
	s_waitcnt vmcnt(0)
	v_pk_add_f32 v[8:9], v[8:9], 1.0 op_sel_hi:[1,0]
	v_pk_add_f32 v[10:11], v[10:11], 1.0 op_sel_hi:[1,0]
	v_pk_fma_f32 v[0:1], v[0:1], v[8:9], v[4:5]
	v_pk_fma_f32 v[2:3], v[2:3], v[10:11], v[6:7]
	v_bfe_u32 v4, v0, 16, 1
	v_add3_u32 v0, v0, v4, s24
	v_bfe_u32 v4, v1, 16, 1
	v_lshrrev_b32_e32 v0, 16, v0
	v_add3_u32 v1, v1, v4, s24
	v_and_or_b32 v0, v1, s28, v0
	v_bfe_u32 v1, v2, 16, 1
	v_add3_u32 v1, v2, v1, s24
	v_bfe_u32 v2, v3, 16, 1
	v_lshrrev_b32_e32 v1, 16, v1
	v_add3_u32 v2, v3, v2, s24
	v_and_or_b32 v1, v2, s28, v1
	buffer_store_dwordx2 v[0:1], v153, s[8:11], s31 offen
	buffer_load_dwordx4 v[0:3], v152, s[4:7], s55 offen
	s_nop 0
	buffer_load_dwordx4 v[4:7], v152, s[60:63], s55 offen
	buffer_load_dwordx4 v[8:11], v152, s[56:59], s55 offen
	s_waitcnt vmcnt(2)
	v_pk_mul_f32 v[0:1], v[58:59], v[0:1]
	v_pk_mul_f32 v[2:3], v[56:57], v[2:3]
	s_waitcnt vmcnt(0)
	v_pk_add_f32 v[8:9], v[8:9], 1.0 op_sel_hi:[1,0]
	v_pk_add_f32 v[10:11], v[10:11], 1.0 op_sel_hi:[1,0]
	v_pk_fma_f32 v[0:1], v[0:1], v[8:9], v[4:5]
	v_pk_fma_f32 v[2:3], v[2:3], v[10:11], v[6:7]
	v_bfe_u32 v4, v0, 16, 1
	v_add3_u32 v0, v0, v4, s24
	v_bfe_u32 v4, v1, 16, 1
	v_lshrrev_b32_e32 v0, 16, v0
	v_add3_u32 v1, v1, v4, s24
	v_and_or_b32 v0, v1, s28, v0
	v_bfe_u32 v1, v2, 16, 1
	v_add3_u32 v1, v2, v1, s24
	v_bfe_u32 v2, v3, 16, 1
	v_lshrrev_b32_e32 v1, 16, v1
	v_add3_u32 v2, v3, v2, s24
	v_and_or_b32 v1, v2, s28, v1
	buffer_store_dwordx2 v[0:1], v153, s[8:11], s33 offen
	buffer_load_dwordx4 v[0:3], v152, s[4:7], s76 offen
	s_nop 0
	buffer_load_dwordx4 v[4:7], v152, s[60:63], s76 offen
	buffer_load_dwordx4 v[8:11], v152, s[56:59], s76 offen
	s_waitcnt vmcnt(2)
	v_pk_mul_f32 v[0:1], v[52:53], v[0:1]
	v_pk_mul_f32 v[2:3], v[54:55], v[2:3]
	s_waitcnt vmcnt(0)
	v_pk_add_f32 v[8:9], v[8:9], 1.0 op_sel_hi:[1,0]
	v_pk_add_f32 v[10:11], v[10:11], 1.0 op_sel_hi:[1,0]
	v_pk_fma_f32 v[0:1], v[0:1], v[8:9], v[4:5]
	v_pk_fma_f32 v[2:3], v[2:3], v[10:11], v[6:7]
	v_bfe_u32 v4, v0, 16, 1
	v_add3_u32 v0, v0, v4, s24
	v_bfe_u32 v4, v1, 16, 1
	v_lshrrev_b32_e32 v0, 16, v0
	v_add3_u32 v1, v1, v4, s24
	v_and_or_b32 v0, v1, s28, v0
	v_bfe_u32 v1, v2, 16, 1
	v_add3_u32 v1, v2, v1, s24
	v_bfe_u32 v2, v3, 16, 1
	v_lshrrev_b32_e32 v1, 16, v1
	v_add3_u32 v2, v3, v2, s24
	v_and_or_b32 v1, v2, s28, v1
	buffer_store_dwordx2 v[0:1], v153, s[8:11], s35 offen
	buffer_load_dwordx4 v[0:3], v152, s[4:7], s94 offen
	s_nop 0
	buffer_load_dwordx4 v[4:7], v152, s[60:63], s94 offen
	buffer_load_dwordx4 v[8:11], v152, s[56:59], s94 offen
	s_waitcnt vmcnt(2)
	v_pk_mul_f32 v[0:1], v[50:51], v[0:1]
	v_pk_mul_f32 v[2:3], v[48:49], v[2:3]
	s_waitcnt vmcnt(0)
	v_pk_add_f32 v[8:9], v[8:9], 1.0 op_sel_hi:[1,0]
	v_pk_add_f32 v[10:11], v[10:11], 1.0 op_sel_hi:[1,0]
	v_pk_fma_f32 v[0:1], v[0:1], v[8:9], v[4:5]
	v_pk_fma_f32 v[2:3], v[2:3], v[10:11], v[6:7]
	v_bfe_u32 v4, v0, 16, 1
	v_add3_u32 v0, v0, v4, s24
	v_bfe_u32 v4, v1, 16, 1
	v_lshrrev_b32_e32 v0, 16, v0
	v_add3_u32 v1, v1, v4, s24
	v_and_or_b32 v0, v1, s28, v0
	v_bfe_u32 v1, v2, 16, 1
	v_add3_u32 v1, v2, v1, s24
	v_bfe_u32 v2, v3, 16, 1
	v_lshrrev_b32_e32 v1, 16, v1
	v_add3_u32 v2, v3, v2, s24
	v_and_or_b32 v1, v2, s28, v1
	buffer_store_dwordx2 v[0:1], v153, s[8:11], s53 offen
	buffer_load_dwordx4 v[0:3], v152, s[4:7], s78 offen
	s_nop 0
	buffer_load_dwordx4 v[4:7], v152, s[60:63], s78 offen
	buffer_load_dwordx4 v[8:11], v152, s[56:59], s78 offen
	s_waitcnt vmcnt(2)
	v_pk_mul_f32 v[0:1], v[46:47], v[0:1]
	v_pk_mul_f32 v[2:3], v[44:45], v[2:3]
	s_waitcnt vmcnt(0)
	v_pk_add_f32 v[8:9], v[8:9], 1.0 op_sel_hi:[1,0]
	v_pk_add_f32 v[10:11], v[10:11], 1.0 op_sel_hi:[1,0]
	v_pk_fma_f32 v[0:1], v[0:1], v[8:9], v[4:5]
	v_pk_fma_f32 v[2:3], v[2:3], v[10:11], v[6:7]
	v_bfe_u32 v4, v0, 16, 1
	v_add3_u32 v0, v0, v4, s24
	v_bfe_u32 v4, v1, 16, 1
	v_lshrrev_b32_e32 v0, 16, v0
	v_add3_u32 v1, v1, v4, s24
	v_and_or_b32 v0, v1, s28, v0
	v_bfe_u32 v1, v2, 16, 1
	v_add3_u32 v1, v2, v1, s24
	v_bfe_u32 v2, v3, 16, 1
	v_lshrrev_b32_e32 v1, 16, v1
	v_add3_u32 v2, v3, v2, s24
	v_and_or_b32 v1, v2, s28, v1
	buffer_store_dwordx2 v[0:1], v153, s[8:11], s54 offen
	buffer_load_dwordx4 v[0:3], v152, s[4:7], s10 offen
	s_nop 0
	buffer_load_dwordx4 v[4:7], v152, s[60:63], s10 offen
	buffer_load_dwordx4 v[8:11], v152, s[56:59], s10 offen
	s_waitcnt vmcnt(2)
	v_pk_mul_f32 v[0:1], v[40:41], v[0:1]
	v_pk_mul_f32 v[2:3], v[42:43], v[2:3]
	s_waitcnt vmcnt(0)
	v_pk_add_f32 v[8:9], v[8:9], 1.0 op_sel_hi:[1,0]
	v_pk_add_f32 v[10:11], v[10:11], 1.0 op_sel_hi:[1,0]
	v_pk_fma_f32 v[0:1], v[0:1], v[8:9], v[4:5]
	v_pk_fma_f32 v[2:3], v[2:3], v[10:11], v[6:7]
	v_bfe_u32 v4, v0, 16, 1
	v_add3_u32 v0, v0, v4, s24
	v_bfe_u32 v4, v1, 16, 1
	v_lshrrev_b32_e32 v0, 16, v0
	v_add3_u32 v1, v1, v4, s24
	v_and_or_b32 v0, v1, s28, v0
	v_bfe_u32 v1, v2, 16, 1
	v_add3_u32 v1, v2, v1, s24
	v_bfe_u32 v2, v3, 16, 1
	v_lshrrev_b32_e32 v1, 16, v1
	v_add3_u32 v2, v3, v2, s24
	v_and_or_b32 v1, v2, s28, v1
	buffer_store_dwordx2 v[0:1], v153, s[8:11], s55 offen
	buffer_load_dwordx4 v[8:11], v152, s[4:7], s88 offen
	s_nop 0
	buffer_load_dwordx4 v[0:3], v152, s[60:63], s88 offen
	buffer_load_dwordx4 v[4:7], v152, s[56:59], s88 offen
	s_waitcnt vmcnt(2)
	v_pk_mul_f32 v[8:9], v[38:39], v[8:9]
	v_pk_mul_f32 v[10:11], v[36:37], v[10:11]
	s_waitcnt vmcnt(0)
	v_pk_add_f32 v[4:5], v[4:5], 1.0 op_sel_hi:[1,0]
	v_pk_add_f32 v[6:7], v[6:7], 1.0 op_sel_hi:[1,0]
	v_pk_fma_f32 v[0:1], v[8:9], v[4:5], v[0:1]
	v_pk_fma_f32 v[2:3], v[10:11], v[6:7], v[2:3]
	v_bfe_u32 v4, v0, 16, 1
	v_add3_u32 v0, v0, v4, s24
	v_bfe_u32 v4, v1, 16, 1
	v_lshrrev_b32_e32 v0, 16, v0
	v_add3_u32 v1, v1, v4, s24
	v_and_or_b32 v0, v1, s28, v0
	v_bfe_u32 v1, v2, 16, 1
	v_add3_u32 v1, v2, v1, s24
	v_bfe_u32 v2, v3, 16, 1
	v_lshrrev_b32_e32 v1, 16, v1
	v_add3_u32 v2, v3, v2, s24
	v_and_or_b32 v1, v2, s28, v1
	buffer_store_dwordx2 v[0:1], v153, s[8:11], s73 offen
	buffer_load_dwordx4 v[0:3], v152, s[4:7], s89 offen
	s_nop 0
	buffer_load_dwordx4 v[4:7], v152, s[60:63], s89 offen
	buffer_load_dwordx4 v[8:11], v152, s[56:59], s89 offen
	s_waitcnt vmcnt(2)
	v_pk_mul_f32 v[0:1], v[34:35], v[0:1]
	v_pk_mul_f32 v[2:3], v[32:33], v[2:3]
	s_waitcnt vmcnt(0)
	v_pk_add_f32 v[8:9], v[8:9], 1.0 op_sel_hi:[1,0]
	v_pk_add_f32 v[10:11], v[10:11], 1.0 op_sel_hi:[1,0]
	v_pk_fma_f32 v[0:1], v[0:1], v[8:9], v[4:5]
	v_pk_fma_f32 v[2:3], v[2:3], v[10:11], v[6:7]
	v_bfe_u32 v4, v0, 16, 1
	v_add3_u32 v0, v0, v4, s24
	v_bfe_u32 v4, v1, 16, 1
	v_lshrrev_b32_e32 v0, 16, v0
	v_add3_u32 v1, v1, v4, s24
	v_and_or_b32 v0, v1, s28, v0
	v_bfe_u32 v1, v2, 16, 1
	v_add3_u32 v1, v2, v1, s24
	v_bfe_u32 v2, v3, 16, 1
	v_lshrrev_b32_e32 v1, 16, v1
	v_add3_u32 v2, v3, v2, s24
	v_and_or_b32 v1, v2, s28, v1
	buffer_store_dwordx2 v[0:1], v153, s[8:11], s76 offen
	buffer_load_dwordx4 v[0:3], v152, s[4:7], s82 offen
	s_nop 0
	buffer_load_dwordx4 v[4:7], v152, s[60:63], s82 offen
	buffer_load_dwordx4 v[8:11], v152, s[56:59], s82 offen
	s_waitcnt vmcnt(2)
	v_pk_mul_f32 v[0:1], v[28:29], v[0:1]
	v_pk_mul_f32 v[2:3], v[30:31], v[2:3]
	s_waitcnt vmcnt(0)
	v_pk_add_f32 v[8:9], v[8:9], 1.0 op_sel_hi:[1,0]
	v_pk_add_f32 v[10:11], v[10:11], 1.0 op_sel_hi:[1,0]
	v_pk_fma_f32 v[0:1], v[0:1], v[8:9], v[4:5]
	v_pk_fma_f32 v[2:3], v[2:3], v[10:11], v[6:7]
	v_bfe_u32 v4, v0, 16, 1
	v_add3_u32 v0, v0, v4, s24
	v_bfe_u32 v4, v1, 16, 1
	v_lshrrev_b32_e32 v0, 16, v0
	v_add3_u32 v1, v1, v4, s24
	v_and_or_b32 v0, v1, s28, v0
	v_bfe_u32 v1, v2, 16, 1
	v_add3_u32 v1, v2, v1, s24
	v_bfe_u32 v2, v3, 16, 1
	v_lshrrev_b32_e32 v1, 16, v1
	v_add3_u32 v2, v3, v2, s24
	v_and_or_b32 v1, v2, s28, v1
	buffer_store_dwordx2 v[0:1], v153, s[8:11], s77 offen
	buffer_load_dwordx4 v[0:3], v152, s[4:7], s83 offen
	s_nop 0
	buffer_load_dwordx4 v[4:7], v152, s[60:63], s83 offen
	buffer_load_dwordx4 v[8:11], v152, s[56:59], s83 offen
	s_waitcnt vmcnt(2)
	v_pk_mul_f32 v[0:1], v[26:27], v[0:1]
	v_pk_mul_f32 v[2:3], v[24:25], v[2:3]
	s_waitcnt vmcnt(0)
	v_pk_add_f32 v[8:9], v[8:9], 1.0 op_sel_hi:[1,0]
	v_pk_add_f32 v[10:11], v[10:11], 1.0 op_sel_hi:[1,0]
	v_pk_fma_f32 v[0:1], v[0:1], v[8:9], v[4:5]
	v_pk_fma_f32 v[2:3], v[2:3], v[10:11], v[6:7]
	v_bfe_u32 v4, v0, 16, 1
	v_add3_u32 v0, v0, v4, s24
	v_bfe_u32 v4, v1, 16, 1
	v_lshrrev_b32_e32 v0, 16, v0
	v_add3_u32 v1, v1, v4, s24
	v_and_or_b32 v0, v1, s28, v0
	v_bfe_u32 v1, v2, 16, 1
	v_add3_u32 v1, v2, v1, s24
	v_bfe_u32 v2, v3, 16, 1
	v_lshrrev_b32_e32 v1, 16, v1
	v_add3_u32 v2, v3, v2, s24
	v_and_or_b32 v1, v2, s28, v1
	buffer_store_dwordx2 v[0:1], v153, s[8:11], s94 offen
	buffer_load_dwordx4 v[0:3], v152, s[4:7], s96 offen
	s_nop 0
	buffer_load_dwordx4 v[4:7], v152, s[60:63], s96 offen
	buffer_load_dwordx4 v[8:11], v152, s[56:59], s96 offen
	s_waitcnt vmcnt(2)
	v_pk_mul_f32 v[0:1], v[22:23], v[0:1]
	v_pk_mul_f32 v[2:3], v[20:21], v[2:3]
	s_waitcnt vmcnt(0)
	v_pk_add_f32 v[8:9], v[8:9], 1.0 op_sel_hi:[1,0]
	v_pk_add_f32 v[10:11], v[10:11], 1.0 op_sel_hi:[1,0]
	v_pk_fma_f32 v[0:1], v[0:1], v[8:9], v[4:5]
	v_pk_fma_f32 v[2:3], v[2:3], v[10:11], v[6:7]
	v_bfe_u32 v4, v0, 16, 1
	v_add3_u32 v0, v0, v4, s24
	v_bfe_u32 v4, v1, 16, 1
	v_lshrrev_b32_e32 v0, 16, v0
	v_add3_u32 v1, v1, v4, s24
	v_and_or_b32 v0, v1, s28, v0
	v_bfe_u32 v1, v2, 16, 1
	v_add3_u32 v1, v2, v1, s24
	v_bfe_u32 v2, v3, 16, 1
	v_lshrrev_b32_e32 v1, 16, v1
	v_add3_u32 v2, v3, v2, s24
	v_and_or_b32 v1, v2, s28, v1
	buffer_store_dwordx2 v[0:1], v153, s[8:11], s95 offen
	buffer_load_dwordx4 v[0:3], v152, s[4:7], s97 offen
	s_nop 0
	buffer_load_dwordx4 v[4:7], v152, s[60:63], s97 offen
	buffer_load_dwordx4 v[8:11], v152, s[56:59], s97 offen
	s_waitcnt vmcnt(2)
	v_pk_mul_f32 v[0:1], v[16:17], v[0:1]
	v_pk_mul_f32 v[2:3], v[18:19], v[2:3]
	s_waitcnt vmcnt(0)
	v_pk_add_f32 v[8:9], v[8:9], 1.0 op_sel_hi:[1,0]
	v_pk_add_f32 v[10:11], v[10:11], 1.0 op_sel_hi:[1,0]
	v_pk_fma_f32 v[0:1], v[0:1], v[8:9], v[4:5]
	v_pk_fma_f32 v[2:3], v[2:3], v[10:11], v[6:7]
	v_bfe_u32 v4, v0, 16, 1
	v_add3_u32 v0, v0, v4, s24
	v_bfe_u32 v4, v1, 16, 1
	v_lshrrev_b32_e32 v0, 16, v0
	v_add3_u32 v1, v1, v4, s24
	v_and_or_b32 v0, v1, s28, v0
	v_bfe_u32 v1, v2, 16, 1
	v_add3_u32 v1, v2, v1, s24
	v_bfe_u32 v2, v3, 16, 1
	v_lshrrev_b32_e32 v1, 16, v1
	v_add3_u32 v2, v3, v2, s24
	v_and_or_b32 v1, v2, s28, v1
	buffer_store_dwordx2 v[0:1], v153, s[8:11], s78 offen
	buffer_load_dwordx4 v[0:3], v152, s[4:7], s81 offen
	s_nop 0
	buffer_load_dwordx4 v[4:7], v152, s[60:63], s81 offen
	buffer_load_dwordx4 v[8:11], v152, s[56:59], s81 offen
	s_waitcnt vmcnt(2)
	v_pk_mul_f32 v[0:1], v[14:15], v[0:1]
	v_pk_mul_f32 v[2:3], v[12:13], v[2:3]
	s_waitcnt vmcnt(0)
	v_pk_add_f32 v[8:9], v[8:9], 1.0 op_sel_hi:[1,0]
	v_pk_add_f32 v[10:11], v[10:11], 1.0 op_sel_hi:[1,0]
	v_pk_fma_f32 v[0:1], v[0:1], v[8:9], v[4:5]
	v_pk_fma_f32 v[2:3], v[2:3], v[10:11], v[6:7]
	v_bfe_u32 v4, v0, 16, 1
	v_add3_u32 v0, v0, v4, s24
	v_bfe_u32 v4, v1, 16, 1
	v_lshrrev_b32_e32 v0, 16, v0
	v_add3_u32 v1, v1, v4, s24
	v_and_or_b32 v0, v1, s28, v0
	v_bfe_u32 v1, v2, 16, 1
	v_add3_u32 v1, v2, v1, s24
	v_bfe_u32 v2, v3, 16, 1
	v_lshrrev_b32_e32 v1, 16, v1
	v_add3_u32 v2, v3, v2, s24
	v_and_or_b32 v1, v2, s28, v1
	buffer_store_dwordx2 v[0:1], v153, s[8:11], s79 offen
	s_cbranch_scc1 .LBB0_322
